# P8 merged-slot loop with accumulator-chained MFMA order (m,n,k): same acc back-to-back
# speedup vs baseline: 1.0561x; 1.0561x over previous
; #define PG8_STAGE(bufoff, gbase, voff) do { _Pragma("unroll") for (int _i = 0; _i < 2; ++_i) \
;         __builtin_amdgcn_global_load_lds((const unsigned*)((const char*)(gbase) + (voff)[_i]), (PG8_LAS unsigned*)(lds + (bufoff) + ldsw + _i * 8192), 16, 0, 0); } while (0)
; #define PG8_LDA(dst, b, h) do { _Pragma("unroll") for (int m = 0; m < 4; ++m) _Pragma("unroll") for (int k = 0; k < 2; ++k) dst[m][k] = *(const PG8_LAS bf16x8*)(lds + PG8_SA(b, h) + aoff + m * 2048 + k * 1024); } while (0)
; #define PG8_LDB(dst, b, h) do { _Pragma("unroll") for (int n = 0; n < 2; ++n) _Pragma("unroll") for (int k = 0; k < 2; ++k) dst[n][k] = *(const PG8_LAS bf16x8*)(lds + PG8_SB(b, h) + boff + n * 2048 + k * 1024); } while (0)
; #define PG8_MMA(ai, bj, At, Bt) do { __builtin_amdgcn_s_setprio(1); _Pragma("unroll") for (int m = 0; m < 4; ++m) _Pragma("unroll") for (int n = 0; n < 2; ++n) _Pragma("unroll") for (int k = 0; k < 2; ++k) \
;         acc[ai][bj][m][n] = __builtin_amdgcn_mfma_f32_16x16x32_bf16(Bt[n][k], At[m][k], acc[ai][bj][m][n], 0, 0, 0); __builtin_amdgcn_s_setprio(0); } while (0)
; #define PG8_WAIT_V(n) asm volatile("s_waitcnt vmcnt(" #n ")" ::: "memory")
; template <class Epi, class Sched, bool ALIGN_EPI>
; __device__ __forceinline__ void gemm_phase(PG8_LAS unsigned char* lds, const Gemm g, const Sched& S, const Epi& E) {
;     ...
;             PG8_LDB(B0, 0, 0); PG8_LDB(B1, 0, 1); PG8_SCHED; PG8_LDA(At, 0, 0); PG8_STAGE(PG8_SA(1, 1), a1 + hstepA, voffA);
;             PG8_WAIT_V(8); PG8_WAIT_L(0); PG8_BAR; PG8_MMA(0, 0, At, B0); PG8_MMA(0, 1, At, B1); PG8_BAR; PG8_SCHED;
;             PG8_LDA(At, 0, 1); PG8_STAGE(PG8_SB(0, 0), b2, voffB); PG8_STAGE(PG8_SB(0, 1), b2 + hstepB, voffB); PG8_STAGE(PG8_SA(0, 0), a2, voffA);
;             PG8_WAIT_V(8); PG8_WAIT_L(0); PG8_BAR; PG8_MMA(1, 0, At, B0); PG8_MMA(1, 1, At, B1); PG8_BAR; PG8_SCHED;
;             PG8_LDB(B0, 1, 0); PG8_LDB(B1, 1, 1); PG8_SCHED; PG8_LDA(At, 1, 0); PG8_STAGE(PG8_SA(0, 1), a2 + hstepA, voffA);
;             PG8_WAIT_V(8); PG8_WAIT_L(0); PG8_BAR; PG8_MMA(0, 0, At, B0); PG8_MMA(0, 1, At, B1); PG8_BAR; PG8_SCHED;
;             PG8_LDA(At, 1, 1); PG8_STAGE(PG8_SB(1, 0), b3, voffB); PG8_STAGE(PG8_SB(1, 1), b3 + hstepB, voffB); PG8_STAGE(PG8_SA(1, 0), a3, voffA);
;             PG8_WAIT_V(8); PG8_WAIT_L(0); PG8_BAR; PG8_MMA(1, 0, At, B0); PG8_MMA(1, 1, At, B1); PG8_BAR; PG8_SCHED;
.Lp8k_A_loop:
	s_add_i32 m0, s2, 0x18000
	s_nop 0
	global_load_lds_dwordx4 v134, s[28:29]
	s_add_i32 m0, s2, 0x1a000
	s_nop 0
	global_load_lds_dwordx4 v130, s[28:29]
	s_add_u32 s30, s28, 0x20000
	s_addc_u32 s31, s29, 0
	s_add_i32 m0, s2, 0x19000
	s_nop 0
	global_load_lds_dwordx4 v134, s[30:31]
	s_add_i32 m0, s2, 0x1b000
	s_nop 0
	global_load_lds_dwordx4 v130, s[30:31]
	s_add_u32 s30, s28, 0x80000
	s_addc_u32 s31, s29, 0
	s_add_i32 m0, s2, 0x1c000
	s_nop 0
	global_load_lds_dwordx4 v134, s[30:31]
	s_add_i32 m0, s2, 0x1e000
	s_nop 0
	global_load_lds_dwordx4 v130, s[30:31]
	s_add_u32 s30, s28, 0xa0000
	s_addc_u32 s31, s29, 0
	s_add_i32 m0, s2, 0x1d000
	s_nop 0
	global_load_lds_dwordx4 v134, s[30:31]
	s_add_i32 m0, s2, 0x1f000
	s_nop 0
	global_load_lds_dwordx4 v130, s[30:31]
	s_add_u32 s28, s28, 0x80
	s_addc_u32 s29, s29, 0
	ds_read_b128 v[190:193], v155 offset:0
	ds_read_b128 v[194:197], v155 offset:1024
	ds_read_b128 v[198:201], v155 offset:2048
	ds_read_b128 v[202:205], v155 offset:3072
	ds_read_b128 v[206:209], v155 offset:4096
	ds_read_b128 v[210:213], v155 offset:5120
	ds_read_b128 v[214:217], v155 offset:6144
	ds_read_b128 v[218:221], v155 offset:7168
	ds_read_b128 v[156:159], v153 offset:0
	ds_read_b128 v[160:163], v153 offset:1024
	ds_read_b128 v[164:167], v153 offset:2048
	ds_read_b128 v[168:171], v153 offset:3072
	ds_read_b128 v[174:177], v153 offset:16384
	ds_read_b128 v[178:181], v153 offset:17408
	ds_read_b128 v[182:185], v153 offset:18432
	ds_read_b128 v[186:189], v153 offset:19456
	ds_read_b128 v[222:225], v155 offset:16384
	ds_read_b128 v[226:229], v155 offset:17408
	ds_read_b128 v[230:233], v155 offset:18432
	ds_read_b128 v[234:237], v155 offset:19456
	ds_read_b128 v[238:241], v155 offset:20480
	ds_read_b128 v[242:245], v155 offset:21504
	ds_read_b128 v[246:249], v155 offset:22528
	ds_read_b128 v[250:253], v155 offset:23552
	s_waitcnt vmcnt(8) lgkmcnt(0)
	s_barrier
	s_setprio 1
	v_mfma_f32_16x16x32_bf16 v[126:129], v[156:159], v[190:193], v[126:129]
	v_mfma_f32_16x16x32_bf16 v[126:129], v[160:163], v[194:197], v[126:129]
	v_mfma_f32_16x16x32_bf16 v[122:125], v[164:167], v[190:193], v[122:125]
	v_mfma_f32_16x16x32_bf16 v[122:125], v[168:171], v[194:197], v[122:125]
	v_mfma_f32_16x16x32_bf16 v[110:113], v[156:159], v[198:201], v[110:113]
	v_mfma_f32_16x16x32_bf16 v[110:113], v[160:163], v[202:205], v[110:113]
	v_mfma_f32_16x16x32_bf16 v[106:109], v[164:167], v[198:201], v[106:109]
	v_mfma_f32_16x16x32_bf16 v[106:109], v[168:171], v[202:205], v[106:109]
	v_mfma_f32_16x16x32_bf16 v[94:97], v[156:159], v[206:209], v[94:97]
	v_mfma_f32_16x16x32_bf16 v[94:97], v[160:163], v[210:213], v[94:97]
	v_mfma_f32_16x16x32_bf16 v[90:93], v[164:167], v[206:209], v[90:93]
	v_mfma_f32_16x16x32_bf16 v[90:93], v[168:171], v[210:213], v[90:93]
	v_mfma_f32_16x16x32_bf16 v[78:81], v[156:159], v[214:217], v[78:81]
	v_mfma_f32_16x16x32_bf16 v[78:81], v[160:163], v[218:221], v[78:81]
	v_mfma_f32_16x16x32_bf16 v[74:77], v[164:167], v[214:217], v[74:77]
	v_mfma_f32_16x16x32_bf16 v[74:77], v[168:171], v[218:221], v[74:77]
	v_mfma_f32_16x16x32_bf16 v[118:121], v[174:177], v[190:193], v[118:121]
	v_mfma_f32_16x16x32_bf16 v[118:121], v[178:181], v[194:197], v[118:121]
	v_mfma_f32_16x16x32_bf16 v[114:117], v[182:185], v[190:193], v[114:117]
	v_mfma_f32_16x16x32_bf16 v[114:117], v[186:189], v[194:197], v[114:117]
	v_mfma_f32_16x16x32_bf16 v[102:105], v[174:177], v[198:201], v[102:105]
	v_mfma_f32_16x16x32_bf16 v[102:105], v[178:181], v[202:205], v[102:105]
	v_mfma_f32_16x16x32_bf16 v[98:101], v[182:185], v[198:201], v[98:101]
	v_mfma_f32_16x16x32_bf16 v[98:101], v[186:189], v[202:205], v[98:101]
	v_mfma_f32_16x16x32_bf16 v[86:89], v[174:177], v[206:209], v[86:89]
	v_mfma_f32_16x16x32_bf16 v[86:89], v[178:181], v[210:213], v[86:89]
	v_mfma_f32_16x16x32_bf16 v[82:85], v[182:185], v[206:209], v[82:85]
	v_mfma_f32_16x16x32_bf16 v[82:85], v[186:189], v[210:213], v[82:85]
	v_mfma_f32_16x16x32_bf16 v[70:73], v[174:177], v[214:217], v[70:73]
	v_mfma_f32_16x16x32_bf16 v[70:73], v[178:181], v[218:221], v[70:73]
	v_mfma_f32_16x16x32_bf16 v[66:69], v[182:185], v[214:217], v[66:69]
	v_mfma_f32_16x16x32_bf16 v[66:69], v[186:189], v[218:221], v[66:69]
	v_mfma_f32_16x16x32_bf16 v[62:65], v[156:159], v[222:225], v[62:65]
	v_mfma_f32_16x16x32_bf16 v[62:65], v[160:163], v[226:229], v[62:65]
	v_mfma_f32_16x16x32_bf16 v[58:61], v[164:167], v[222:225], v[58:61]
	v_mfma_f32_16x16x32_bf16 v[58:61], v[168:171], v[226:229], v[58:61]
	v_mfma_f32_16x16x32_bf16 v[46:49], v[156:159], v[230:233], v[46:49]
	v_mfma_f32_16x16x32_bf16 v[46:49], v[160:163], v[234:237], v[46:49]
	v_mfma_f32_16x16x32_bf16 v[42:45], v[164:167], v[230:233], v[42:45]
	v_mfma_f32_16x16x32_bf16 v[42:45], v[168:171], v[234:237], v[42:45]
	v_mfma_f32_16x16x32_bf16 v[30:33], v[156:159], v[238:241], v[30:33]
	v_mfma_f32_16x16x32_bf16 v[30:33], v[160:163], v[242:245], v[30:33]
	v_mfma_f32_16x16x32_bf16 v[26:29], v[164:167], v[238:241], v[26:29]
	v_mfma_f32_16x16x32_bf16 v[26:29], v[168:171], v[242:245], v[26:29]
	v_mfma_f32_16x16x32_bf16 v[14:17], v[156:159], v[246:249], v[14:17]
	v_mfma_f32_16x16x32_bf16 v[14:17], v[160:163], v[250:253], v[14:17]
	v_mfma_f32_16x16x32_bf16 v[10:13], v[164:167], v[246:249], v[10:13]
	v_mfma_f32_16x16x32_bf16 v[10:13], v[168:171], v[250:253], v[10:13]
	v_mfma_f32_16x16x32_bf16 v[54:57], v[174:177], v[222:225], v[54:57]
	v_mfma_f32_16x16x32_bf16 v[54:57], v[178:181], v[226:229], v[54:57]
	v_mfma_f32_16x16x32_bf16 v[50:53], v[182:185], v[222:225], v[50:53]
	v_mfma_f32_16x16x32_bf16 v[50:53], v[186:189], v[226:229], v[50:53]
	v_mfma_f32_16x16x32_bf16 v[38:41], v[174:177], v[230:233], v[38:41]
	v_mfma_f32_16x16x32_bf16 v[38:41], v[178:181], v[234:237], v[38:41]
	v_mfma_f32_16x16x32_bf16 v[34:37], v[182:185], v[230:233], v[34:37]
	v_mfma_f32_16x16x32_bf16 v[34:37], v[186:189], v[234:237], v[34:37]
	v_mfma_f32_16x16x32_bf16 v[22:25], v[174:177], v[238:241], v[22:25]
	v_mfma_f32_16x16x32_bf16 v[22:25], v[178:181], v[242:245], v[22:25]
	v_mfma_f32_16x16x32_bf16 v[18:21], v[182:185], v[238:241], v[18:21]
	v_mfma_f32_16x16x32_bf16 v[18:21], v[186:189], v[242:245], v[18:21]
	v_mfma_f32_16x16x32_bf16 v[6:9], v[174:177], v[246:249], v[6:9]
	v_mfma_f32_16x16x32_bf16 v[6:9], v[178:181], v[250:253], v[6:9]
	v_mfma_f32_16x16x32_bf16 v[2:5], v[182:185], v[246:249], v[2:5]
	v_mfma_f32_16x16x32_bf16 v[2:5], v[186:189], v[250:253], v[2:5]
	s_setprio 0
	s_waitcnt vmcnt(0)
	s_barrier
; #define PG8_STAGE(bufoff, gbase, voff) do { _Pragma("unroll") for (int _i = 0; _i < 2; ++_i) \
;         __builtin_amdgcn_global_load_lds((const unsigned*)((const char*)(gbase) + (voff)[_i]), (PG8_LAS unsigned*)(lds + (bufoff) + ldsw + _i * 8192), 16, 0, 0); } while (0)
; #define PG8_LDA(dst, b, h) do { _Pragma("unroll") for (int m = 0; m < 4; ++m) _Pragma("unroll") for (int k = 0; k < 2; ++k) dst[m][k] = *(const PG8_LAS bf16x8*)(lds + PG8_SA(b, h) + aoff + m * 2048 + k * 1024); } while (0)
; #define PG8_LDB(dst, b, h) do { _Pragma("unroll") for (int n = 0; n < 2; ++n) _Pragma("unroll") for (int k = 0; k < 2; ++k) dst[n][k] = *(const PG8_LAS bf16x8*)(lds + PG8_SB(b, h) + boff + n * 2048 + k * 1024); } while (0)
; #define PG8_MMA(ai, bj, At, Bt) do { __builtin_amdgcn_s_setprio(1); _Pragma("unroll") for (int m = 0; m < 4; ++m) _Pragma("unroll") for (int n = 0; n < 2; ++n) _Pragma("unroll") for (int k = 0; k < 2; ++k) \
;         acc[ai][bj][m][n] = __builtin_amdgcn_mfma_f32_16x16x32_bf16(Bt[n][k], At[m][k], acc[ai][bj][m][n], 0, 0, 0); __builtin_amdgcn_s_setprio(0); } while (0)
; #define PG8_WAIT_V(n) asm volatile("s_waitcnt vmcnt(" #n ")" ::: "memory")
; template <class Epi, class Sched, bool ALIGN_EPI>
; __device__ __forceinline__ void gemm_phase(PG8_LAS unsigned char* lds, const Gemm g, const Sched& S, const Epi& E) {
;     ...
;             PG8_LDB(B0, 0, 0); PG8_LDB(B1, 0, 1); PG8_SCHED; PG8_LDA(At, 0, 0); PG8_STAGE(PG8_SA(1, 1), a1 + hstepA, voffA);
;             PG8_WAIT_V(8); PG8_WAIT_L(0); PG8_BAR; PG8_MMA(0, 0, At, B0); PG8_MMA(0, 1, At, B1); PG8_BAR; PG8_SCHED;
;             PG8_LDA(At, 0, 1); PG8_STAGE(PG8_SB(0, 0), b2, voffB); PG8_STAGE(PG8_SB(0, 1), b2 + hstepB, voffB); PG8_STAGE(PG8_SA(0, 0), a2, voffA);
;             PG8_WAIT_V(8); PG8_WAIT_L(0); PG8_BAR; PG8_MMA(1, 0, At, B0); PG8_MMA(1, 1, At, B1); PG8_BAR; PG8_SCHED;
;             PG8_LDB(B0, 1, 0); PG8_LDB(B1, 1, 1); PG8_SCHED; PG8_LDA(At, 1, 0); PG8_STAGE(PG8_SA(0, 1), a2 + hstepA, voffA);
;             PG8_WAIT_V(8); PG8_WAIT_L(0); PG8_BAR; PG8_MMA(0, 0, At, B0); PG8_MMA(0, 1, At, B1); PG8_BAR; PG8_SCHED;
;             PG8_LDA(At, 1, 1); PG8_STAGE(PG8_SB(1, 0), b3, voffB); PG8_STAGE(PG8_SB(1, 1), b3 + hstepB, voffB); PG8_STAGE(PG8_SA(1, 0), a3, voffA);
;             PG8_WAIT_V(8); PG8_WAIT_L(0); PG8_BAR; PG8_MMA(1, 0, At, B0); PG8_MMA(1, 1, At, B1); PG8_BAR; PG8_SCHED;
	s_cmp_eq_u32 s49, 15
	s_cselect_b32 s28, s50, s28
	s_cselect_b32 s29, s51, s29
	s_add_i32 m0, s2, 0x10000
	s_nop 0
	global_load_lds_dwordx4 v134, s[28:29]
	s_add_i32 m0, s2, 0x12000
	s_nop 0
	global_load_lds_dwordx4 v130, s[28:29]
	s_add_u32 s30, s28, 0x20000
	s_addc_u32 s31, s29, 0
	s_add_i32 m0, s2, 0x11000
	s_nop 0
	global_load_lds_dwordx4 v134, s[30:31]
	s_add_i32 m0, s2, 0x13000
	s_nop 0
	global_load_lds_dwordx4 v130, s[30:31]
	s_add_u32 s30, s28, 0x80000
	s_addc_u32 s31, s29, 0
	s_add_i32 m0, s2, 0x14000
	s_nop 0
	global_load_lds_dwordx4 v134, s[30:31]
	s_add_i32 m0, s2, 0x16000
	s_nop 0
	global_load_lds_dwordx4 v130, s[30:31]
	s_add_u32 s30, s28, 0xa0000
	s_addc_u32 s31, s29, 0
	s_add_i32 m0, s2, 0x15000
	s_nop 0
	global_load_lds_dwordx4 v134, s[30:31]
	s_add_i32 m0, s2, 0x17000
	s_nop 0
	global_load_lds_dwordx4 v130, s[30:31]
	s_add_u32 s28, s28, 0x80
	s_addc_u32 s29, s29, 0
	ds_read_b128 v[190:193], v155 offset:32768
	ds_read_b128 v[194:197], v155 offset:33792
	ds_read_b128 v[198:201], v155 offset:34816
	ds_read_b128 v[202:205], v155 offset:35840
	ds_read_b128 v[206:209], v155 offset:36864
	ds_read_b128 v[210:213], v155 offset:37888
	ds_read_b128 v[214:217], v155 offset:38912
	ds_read_b128 v[218:221], v155 offset:39936
	ds_read_b128 v[156:159], v153 offset:32768
	ds_read_b128 v[160:163], v153 offset:33792
	ds_read_b128 v[164:167], v153 offset:34816
	ds_read_b128 v[168:171], v153 offset:35840
	ds_read_b128 v[174:177], v153 offset:49152
	ds_read_b128 v[178:181], v153 offset:50176
	ds_read_b128 v[182:185], v153 offset:51200
	ds_read_b128 v[186:189], v153 offset:52224
	ds_read_b128 v[222:225], v155 offset:49152
	ds_read_b128 v[226:229], v155 offset:50176
	ds_read_b128 v[230:233], v155 offset:51200
	ds_read_b128 v[234:237], v155 offset:52224
	ds_read_b128 v[238:241], v155 offset:53248
	ds_read_b128 v[242:245], v155 offset:54272
	ds_read_b128 v[246:249], v155 offset:55296
	ds_read_b128 v[250:253], v155 offset:56320
	s_waitcnt vmcnt(8) lgkmcnt(0)
	s_barrier
	s_setprio 1
	v_mfma_f32_16x16x32_bf16 v[126:129], v[156:159], v[190:193], v[126:129]
	v_mfma_f32_16x16x32_bf16 v[126:129], v[160:163], v[194:197], v[126:129]
	v_mfma_f32_16x16x32_bf16 v[122:125], v[164:167], v[190:193], v[122:125]
	v_mfma_f32_16x16x32_bf16 v[122:125], v[168:171], v[194:197], v[122:125]
	v_mfma_f32_16x16x32_bf16 v[110:113], v[156:159], v[198:201], v[110:113]
	v_mfma_f32_16x16x32_bf16 v[110:113], v[160:163], v[202:205], v[110:113]
	v_mfma_f32_16x16x32_bf16 v[106:109], v[164:167], v[198:201], v[106:109]
	v_mfma_f32_16x16x32_bf16 v[106:109], v[168:171], v[202:205], v[106:109]
	v_mfma_f32_16x16x32_bf16 v[94:97], v[156:159], v[206:209], v[94:97]
	v_mfma_f32_16x16x32_bf16 v[94:97], v[160:163], v[210:213], v[94:97]
	v_mfma_f32_16x16x32_bf16 v[90:93], v[164:167], v[206:209], v[90:93]
	v_mfma_f32_16x16x32_bf16 v[90:93], v[168:171], v[210:213], v[90:93]
	v_mfma_f32_16x16x32_bf16 v[78:81], v[156:159], v[214:217], v[78:81]
	v_mfma_f32_16x16x32_bf16 v[78:81], v[160:163], v[218:221], v[78:81]
	v_mfma_f32_16x16x32_bf16 v[74:77], v[164:167], v[214:217], v[74:77]
	v_mfma_f32_16x16x32_bf16 v[74:77], v[168:171], v[218:221], v[74:77]
	v_mfma_f32_16x16x32_bf16 v[118:121], v[174:177], v[190:193], v[118:121]
	v_mfma_f32_16x16x32_bf16 v[118:121], v[178:181], v[194:197], v[118:121]
	v_mfma_f32_16x16x32_bf16 v[114:117], v[182:185], v[190:193], v[114:117]
	v_mfma_f32_16x16x32_bf16 v[114:117], v[186:189], v[194:197], v[114:117]
	v_mfma_f32_16x16x32_bf16 v[102:105], v[174:177], v[198:201], v[102:105]
	v_mfma_f32_16x16x32_bf16 v[102:105], v[178:181], v[202:205], v[102:105]
	v_mfma_f32_16x16x32_bf16 v[98:101], v[182:185], v[198:201], v[98:101]
	v_mfma_f32_16x16x32_bf16 v[98:101], v[186:189], v[202:205], v[98:101]
	v_mfma_f32_16x16x32_bf16 v[86:89], v[174:177], v[206:209], v[86:89]
	v_mfma_f32_16x16x32_bf16 v[86:89], v[178:181], v[210:213], v[86:89]
	v_mfma_f32_16x16x32_bf16 v[82:85], v[182:185], v[206:209], v[82:85]
	v_mfma_f32_16x16x32_bf16 v[82:85], v[186:189], v[210:213], v[82:85]
	v_mfma_f32_16x16x32_bf16 v[70:73], v[174:177], v[214:217], v[70:73]
	v_mfma_f32_16x16x32_bf16 v[70:73], v[178:181], v[218:221], v[70:73]
	v_mfma_f32_16x16x32_bf16 v[66:69], v[182:185], v[214:217], v[66:69]
	v_mfma_f32_16x16x32_bf16 v[66:69], v[186:189], v[218:221], v[66:69]
	v_mfma_f32_16x16x32_bf16 v[62:65], v[156:159], v[222:225], v[62:65]
	v_mfma_f32_16x16x32_bf16 v[62:65], v[160:163], v[226:229], v[62:65]
	v_mfma_f32_16x16x32_bf16 v[58:61], v[164:167], v[222:225], v[58:61]
	v_mfma_f32_16x16x32_bf16 v[58:61], v[168:171], v[226:229], v[58:61]
	v_mfma_f32_16x16x32_bf16 v[46:49], v[156:159], v[230:233], v[46:49]
	v_mfma_f32_16x16x32_bf16 v[46:49], v[160:163], v[234:237], v[46:49]
	v_mfma_f32_16x16x32_bf16 v[42:45], v[164:167], v[230:233], v[42:45]
	v_mfma_f32_16x16x32_bf16 v[42:45], v[168:171], v[234:237], v[42:45]
	v_mfma_f32_16x16x32_bf16 v[30:33], v[156:159], v[238:241], v[30:33]
	v_mfma_f32_16x16x32_bf16 v[30:33], v[160:163], v[242:245], v[30:33]
	v_mfma_f32_16x16x32_bf16 v[26:29], v[164:167], v[238:241], v[26:29]
	v_mfma_f32_16x16x32_bf16 v[26:29], v[168:171], v[242:245], v[26:29]
	v_mfma_f32_16x16x32_bf16 v[14:17], v[156:159], v[246:249], v[14:17]
	v_mfma_f32_16x16x32_bf16 v[14:17], v[160:163], v[250:253], v[14:17]
	v_mfma_f32_16x16x32_bf16 v[10:13], v[164:167], v[246:249], v[10:13]
	v_mfma_f32_16x16x32_bf16 v[10:13], v[168:171], v[250:253], v[10:13]
	v_mfma_f32_16x16x32_bf16 v[54:57], v[174:177], v[222:225], v[54:57]
	v_mfma_f32_16x16x32_bf16 v[54:57], v[178:181], v[226:229], v[54:57]
	v_mfma_f32_16x16x32_bf16 v[50:53], v[182:185], v[222:225], v[50:53]
	v_mfma_f32_16x16x32_bf16 v[50:53], v[186:189], v[226:229], v[50:53]
	v_mfma_f32_16x16x32_bf16 v[38:41], v[174:177], v[230:233], v[38:41]
	v_mfma_f32_16x16x32_bf16 v[38:41], v[178:181], v[234:237], v[38:41]
	v_mfma_f32_16x16x32_bf16 v[34:37], v[182:185], v[230:233], v[34:37]
	v_mfma_f32_16x16x32_bf16 v[34:37], v[186:189], v[234:237], v[34:37]
	v_mfma_f32_16x16x32_bf16 v[22:25], v[174:177], v[238:241], v[22:25]
	v_mfma_f32_16x16x32_bf16 v[22:25], v[178:181], v[242:245], v[22:25]
	v_mfma_f32_16x16x32_bf16 v[18:21], v[182:185], v[238:241], v[18:21]
	v_mfma_f32_16x16x32_bf16 v[18:21], v[186:189], v[242:245], v[18:21]
	v_mfma_f32_16x16x32_bf16 v[6:9], v[174:177], v[246:249], v[6:9]
	v_mfma_f32_16x16x32_bf16 v[6:9], v[178:181], v[250:253], v[6:9]
	v_mfma_f32_16x16x32_bf16 v[2:5], v[182:185], v[246:249], v[2:5]
	v_mfma_f32_16x16x32_bf16 v[2:5], v[186:189], v[250:253], v[2:5]
	s_setprio 0
	s_waitcnt vmcnt(0)
	s_barrier
	s_add_i32 s49, s49, 1
	s_cmp_lt_u32 s49, 16
	s_cbranch_scc1 .Lp8k_A_loop
	s_branch .Lp8k_done

; #define PG8_STAGE(bufoff, gbase, voff) do { _Pragma("unroll") for (int _i = 0; _i < 2; ++_i) \
;         __builtin_amdgcn_global_load_lds((const unsigned*)((const char*)(gbase) + (voff)[_i]), (PG8_LAS unsigned*)(lds + (bufoff) + ldsw + _i * 8192), 16, 0, 0); } while (0)
; #define PG8_LDA(dst, b, h) do { _Pragma("unroll") for (int m = 0; m < 4; ++m) _Pragma("unroll") for (int k = 0; k < 2; ++k) dst[m][k] = *(const PG8_LAS bf16x8*)(lds + PG8_SA(b, h) + aoff + m * 2048 + k * 1024); } while (0)
; #define PG8_LDB(dst, b, h) do { _Pragma("unroll") for (int n = 0; n < 2; ++n) _Pragma("unroll") for (int k = 0; k < 2; ++k) dst[n][k] = *(const PG8_LAS bf16x8*)(lds + PG8_SB(b, h) + boff + n * 2048 + k * 1024); } while (0)
; #define PG8_MMA(ai, bj, At, Bt) do { __builtin_amdgcn_s_setprio(1); _Pragma("unroll") for (int m = 0; m < 4; ++m) _Pragma("unroll") for (int n = 0; n < 2; ++n) _Pragma("unroll") for (int k = 0; k < 2; ++k) \
;         acc[ai][bj][m][n] = __builtin_amdgcn_mfma_f32_16x16x32_bf16(Bt[n][k], At[m][k], acc[ai][bj][m][n], 0, 0, 0); __builtin_amdgcn_s_setprio(0); } while (0)
; #define PG8_WAIT_V(n) asm volatile("s_waitcnt vmcnt(" #n ")" ::: "memory")
; template <class Epi, class Sched, bool ALIGN_EPI>
; __device__ __forceinline__ void gemm_phase(PG8_LAS unsigned char* lds, const Gemm g, const Sched& S, const Epi& E) {
;     ...
;             PG8_LDB(B0, 0, 0); PG8_LDB(B1, 0, 1); PG8_SCHED; PG8_LDA(At, 0, 0); PG8_STAGE(PG8_SA(1, 1), a1 + hstepA, voffA);
;             PG8_WAIT_V(8); PG8_WAIT_L(0); PG8_BAR; PG8_MMA(0, 0, At, B0); PG8_MMA(0, 1, At, B1); PG8_BAR; PG8_SCHED;
;             PG8_LDA(At, 0, 1); PG8_STAGE(PG8_SB(0, 0), b2, voffB); PG8_STAGE(PG8_SB(0, 1), b2 + hstepB, voffB); PG8_STAGE(PG8_SA(0, 0), a2, voffA);
;             PG8_WAIT_V(8); PG8_WAIT_L(0); PG8_BAR; PG8_MMA(1, 0, At, B0); PG8_MMA(1, 1, At, B1); PG8_BAR; PG8_SCHED;
;             PG8_LDB(B0, 1, 0); PG8_LDB(B1, 1, 1); PG8_SCHED; PG8_LDA(At, 1, 0); PG8_STAGE(PG8_SA(0, 1), a2 + hstepA, voffA);
;             PG8_WAIT_V(8); PG8_WAIT_L(0); PG8_BAR; PG8_MMA(0, 0, At, B0); PG8_MMA(0, 1, At, B1); PG8_BAR; PG8_SCHED;
;             PG8_LDA(At, 1, 1); PG8_STAGE(PG8_SB(1, 0), b3, voffB); PG8_STAGE(PG8_SB(1, 1), b3 + hstepB, voffB); PG8_STAGE(PG8_SA(1, 0), a3, voffA);
;             PG8_WAIT_V(8); PG8_WAIT_L(0); PG8_BAR; PG8_MMA(1, 0, At, B0); PG8_MMA(1, 1, At, B1); PG8_BAR; PG8_SCHED;
.Lp8k_B_loop:
	s_add_i32 m0, s2, 0xa000
	s_nop 0
	global_load_lds_dwordx4 v132, s[28:29]
	s_add_u32 s30, s28, 0x20000
	s_addc_u32 s31, s29, 0
	s_add_i32 m0, s2, 0xb000
	s_nop 0
	global_load_lds_dwordx4 v132, s[30:31]
	s_add_u32 s30, s28, 0x80000
	s_addc_u32 s31, s29, 0
	s_add_i32 m0, s2, 0xe000
	s_nop 0
	global_load_lds_dwordx4 v132, s[30:31]
	s_add_u32 s30, s28, 0xa0000
	s_addc_u32 s31, s29, 0
	s_add_i32 m0, s2, 0xf000
	s_nop 0
	global_load_lds_dwordx4 v132, s[30:31]
	s_add_u32 s34, s28, 0x80
	s_addc_u32 s35, s29, 0
	s_cmp_eq_u32 s49, 15
	s_cselect_b32 s34, s50, s34
	s_cselect_b32 s35, s51, s35
	s_add_i32 m0, s2, 0x0
	s_nop 0
	global_load_lds_dwordx4 v136, s[34:35]
	s_add_u32 s30, s34, 0x20000
	s_addc_u32 s31, s35, 0
	s_add_i32 m0, s2, 0x1000
	s_nop 0
	global_load_lds_dwordx4 v136, s[30:31]
	s_add_u32 s30, s34, 0x80000
	s_addc_u32 s31, s35, 0
	s_add_i32 m0, s2, 0x4000
	s_nop 0
	global_load_lds_dwordx4 v136, s[30:31]
	s_add_u32 s30, s34, 0xa0000
	s_addc_u32 s31, s35, 0
	s_add_i32 m0, s2, 0x5000
	s_nop 0
	global_load_lds_dwordx4 v136, s[30:31]
	s_add_u32 s28, s28, 0x80
	s_addc_u32 s29, s29, 0
	ds_read_b128 v[190:193], v155 offset:0
	ds_read_b128 v[194:197], v155 offset:1024
	ds_read_b128 v[198:201], v155 offset:2048
	ds_read_b128 v[202:205], v155 offset:3072
	ds_read_b128 v[206:209], v155 offset:4096
	ds_read_b128 v[210:213], v155 offset:5120
	ds_read_b128 v[214:217], v155 offset:6144
	ds_read_b128 v[218:221], v155 offset:7168
	ds_read_b128 v[156:159], v153 offset:0
	ds_read_b128 v[160:163], v153 offset:1024
	ds_read_b128 v[164:167], v153 offset:2048
	ds_read_b128 v[168:171], v153 offset:3072
	ds_read_b128 v[174:177], v153 offset:16384
	ds_read_b128 v[178:181], v153 offset:17408
	ds_read_b128 v[182:185], v153 offset:18432
	ds_read_b128 v[186:189], v153 offset:19456
	ds_read_b128 v[222:225], v155 offset:16384
	ds_read_b128 v[226:229], v155 offset:17408
	ds_read_b128 v[230:233], v155 offset:18432
	ds_read_b128 v[234:237], v155 offset:19456
	ds_read_b128 v[238:241], v155 offset:20480
	ds_read_b128 v[242:245], v155 offset:21504
	ds_read_b128 v[246:249], v155 offset:22528
	ds_read_b128 v[250:253], v155 offset:23552
	s_waitcnt vmcnt(8) lgkmcnt(0)
	s_barrier
	s_setprio 1
	v_mfma_f32_16x16x32_bf16 v[126:129], v[156:159], v[190:193], v[126:129]
	v_mfma_f32_16x16x32_bf16 v[126:129], v[160:163], v[194:197], v[126:129]
	v_mfma_f32_16x16x32_bf16 v[122:125], v[164:167], v[190:193], v[122:125]
	v_mfma_f32_16x16x32_bf16 v[122:125], v[168:171], v[194:197], v[122:125]
	v_mfma_f32_16x16x32_bf16 v[110:113], v[156:159], v[198:201], v[110:113]
	v_mfma_f32_16x16x32_bf16 v[110:113], v[160:163], v[202:205], v[110:113]
	v_mfma_f32_16x16x32_bf16 v[106:109], v[164:167], v[198:201], v[106:109]
	v_mfma_f32_16x16x32_bf16 v[106:109], v[168:171], v[202:205], v[106:109]
	v_mfma_f32_16x16x32_bf16 v[94:97], v[156:159], v[206:209], v[94:97]
	v_mfma_f32_16x16x32_bf16 v[94:97], v[160:163], v[210:213], v[94:97]
	v_mfma_f32_16x16x32_bf16 v[90:93], v[164:167], v[206:209], v[90:93]
	v_mfma_f32_16x16x32_bf16 v[90:93], v[168:171], v[210:213], v[90:93]
	v_mfma_f32_16x16x32_bf16 v[78:81], v[156:159], v[214:217], v[78:81]
	v_mfma_f32_16x16x32_bf16 v[78:81], v[160:163], v[218:221], v[78:81]
	v_mfma_f32_16x16x32_bf16 v[74:77], v[164:167], v[214:217], v[74:77]
	v_mfma_f32_16x16x32_bf16 v[74:77], v[168:171], v[218:221], v[74:77]
	v_mfma_f32_16x16x32_bf16 v[118:121], v[174:177], v[190:193], v[118:121]
	v_mfma_f32_16x16x32_bf16 v[118:121], v[178:181], v[194:197], v[118:121]
	v_mfma_f32_16x16x32_bf16 v[114:117], v[182:185], v[190:193], v[114:117]
	v_mfma_f32_16x16x32_bf16 v[114:117], v[186:189], v[194:197], v[114:117]
	v_mfma_f32_16x16x32_bf16 v[102:105], v[174:177], v[198:201], v[102:105]
	v_mfma_f32_16x16x32_bf16 v[102:105], v[178:181], v[202:205], v[102:105]
	v_mfma_f32_16x16x32_bf16 v[98:101], v[182:185], v[198:201], v[98:101]
	v_mfma_f32_16x16x32_bf16 v[98:101], v[186:189], v[202:205], v[98:101]
	v_mfma_f32_16x16x32_bf16 v[86:89], v[174:177], v[206:209], v[86:89]
	v_mfma_f32_16x16x32_bf16 v[86:89], v[178:181], v[210:213], v[86:89]
	v_mfma_f32_16x16x32_bf16 v[82:85], v[182:185], v[206:209], v[82:85]
	v_mfma_f32_16x16x32_bf16 v[82:85], v[186:189], v[210:213], v[82:85]
	v_mfma_f32_16x16x32_bf16 v[70:73], v[174:177], v[214:217], v[70:73]
	v_mfma_f32_16x16x32_bf16 v[70:73], v[178:181], v[218:221], v[70:73]
	v_mfma_f32_16x16x32_bf16 v[66:69], v[182:185], v[214:217], v[66:69]
	v_mfma_f32_16x16x32_bf16 v[66:69], v[186:189], v[218:221], v[66:69]
	v_mfma_f32_16x16x32_bf16 v[62:65], v[156:159], v[222:225], v[62:65]
	v_mfma_f32_16x16x32_bf16 v[62:65], v[160:163], v[226:229], v[62:65]
	v_mfma_f32_16x16x32_bf16 v[58:61], v[164:167], v[222:225], v[58:61]
	v_mfma_f32_16x16x32_bf16 v[58:61], v[168:171], v[226:229], v[58:61]
	v_mfma_f32_16x16x32_bf16 v[46:49], v[156:159], v[230:233], v[46:49]
	v_mfma_f32_16x16x32_bf16 v[46:49], v[160:163], v[234:237], v[46:49]
	v_mfma_f32_16x16x32_bf16 v[42:45], v[164:167], v[230:233], v[42:45]
	v_mfma_f32_16x16x32_bf16 v[42:45], v[168:171], v[234:237], v[42:45]
	v_mfma_f32_16x16x32_bf16 v[30:33], v[156:159], v[238:241], v[30:33]
	v_mfma_f32_16x16x32_bf16 v[30:33], v[160:163], v[242:245], v[30:33]
	v_mfma_f32_16x16x32_bf16 v[26:29], v[164:167], v[238:241], v[26:29]
	v_mfma_f32_16x16x32_bf16 v[26:29], v[168:171], v[242:245], v[26:29]
	v_mfma_f32_16x16x32_bf16 v[14:17], v[156:159], v[246:249], v[14:17]
	v_mfma_f32_16x16x32_bf16 v[14:17], v[160:163], v[250:253], v[14:17]
	v_mfma_f32_16x16x32_bf16 v[10:13], v[164:167], v[246:249], v[10:13]
	v_mfma_f32_16x16x32_bf16 v[10:13], v[168:171], v[250:253], v[10:13]
	v_mfma_f32_16x16x32_bf16 v[54:57], v[174:177], v[222:225], v[54:57]
	v_mfma_f32_16x16x32_bf16 v[54:57], v[178:181], v[226:229], v[54:57]
	v_mfma_f32_16x16x32_bf16 v[50:53], v[182:185], v[222:225], v[50:53]
	v_mfma_f32_16x16x32_bf16 v[50:53], v[186:189], v[226:229], v[50:53]
	v_mfma_f32_16x16x32_bf16 v[38:41], v[174:177], v[230:233], v[38:41]
	v_mfma_f32_16x16x32_bf16 v[38:41], v[178:181], v[234:237], v[38:41]
	v_mfma_f32_16x16x32_bf16 v[34:37], v[182:185], v[230:233], v[34:37]
	v_mfma_f32_16x16x32_bf16 v[34:37], v[186:189], v[234:237], v[34:37]
	v_mfma_f32_16x16x32_bf16 v[22:25], v[174:177], v[238:241], v[22:25]
	v_mfma_f32_16x16x32_bf16 v[22:25], v[178:181], v[242:245], v[22:25]
	v_mfma_f32_16x16x32_bf16 v[18:21], v[182:185], v[238:241], v[18:21]
	v_mfma_f32_16x16x32_bf16 v[18:21], v[186:189], v[242:245], v[18:21]
	v_mfma_f32_16x16x32_bf16 v[6:9], v[174:177], v[246:249], v[6:9]
	v_mfma_f32_16x16x32_bf16 v[6:9], v[178:181], v[250:253], v[6:9]
	v_mfma_f32_16x16x32_bf16 v[2:5], v[182:185], v[246:249], v[2:5]
	v_mfma_f32_16x16x32_bf16 v[2:5], v[186:189], v[250:253], v[2:5]
	s_setprio 0
	s_waitcnt vmcnt(0)
	s_barrier
; #define PG8_STAGE(bufoff, gbase, voff) do { _Pragma("unroll") for (int _i = 0; _i < 2; ++_i) \
;         __builtin_amdgcn_global_load_lds((const unsigned*)((const char*)(gbase) + (voff)[_i]), (PG8_LAS unsigned*)(lds + (bufoff) + ldsw + _i * 8192), 16, 0, 0); } while (0)
; #define PG8_LDA(dst, b, h) do { _Pragma("unroll") for (int m = 0; m < 4; ++m) _Pragma("unroll") for (int k = 0; k < 2; ++k) dst[m][k] = *(const PG8_LAS bf16x8*)(lds + PG8_SA(b, h) + aoff + m * 2048 + k * 1024); } while (0)
; #define PG8_LDB(dst, b, h) do { _Pragma("unroll") for (int n = 0; n < 2; ++n) _Pragma("unroll") for (int k = 0; k < 2; ++k) dst[n][k] = *(const PG8_LAS bf16x8*)(lds + PG8_SB(b, h) + boff + n * 2048 + k * 1024); } while (0)
; #define PG8_MMA(ai, bj, At, Bt) do { __builtin_amdgcn_s_setprio(1); _Pragma("unroll") for (int m = 0; m < 4; ++m) _Pragma("unroll") for (int n = 0; n < 2; ++n) _Pragma("unroll") for (int k = 0; k < 2; ++k) \
;         acc[ai][bj][m][n] = __builtin_amdgcn_mfma_f32_16x16x32_bf16(Bt[n][k], At[m][k], acc[ai][bj][m][n], 0, 0, 0); __builtin_amdgcn_s_setprio(0); } while (0)
; #define PG8_WAIT_V(n) asm volatile("s_waitcnt vmcnt(" #n ")" ::: "memory")
; template <class Epi, class Sched, bool ALIGN_EPI>
; __device__ __forceinline__ void gemm_phase(PG8_LAS unsigned char* lds, const Gemm g, const Sched& S, const Epi& E) {
;     ...
;             PG8_LDB(B0, 0, 0); PG8_LDB(B1, 0, 1); PG8_SCHED; PG8_LDA(At, 0, 0); PG8_STAGE(PG8_SA(1, 1), a1 + hstepA, voffA);
;             PG8_WAIT_V(8); PG8_WAIT_L(0); PG8_BAR; PG8_MMA(0, 0, At, B0); PG8_MMA(0, 1, At, B1); PG8_BAR; PG8_SCHED;
;             PG8_LDA(At, 0, 1); PG8_STAGE(PG8_SB(0, 0), b2, voffB); PG8_STAGE(PG8_SB(0, 1), b2 + hstepB, voffB); PG8_STAGE(PG8_SA(0, 0), a2, voffA);
;             PG8_WAIT_V(8); PG8_WAIT_L(0); PG8_BAR; PG8_MMA(1, 0, At, B0); PG8_MMA(1, 1, At, B1); PG8_BAR; PG8_SCHED;
;             PG8_LDB(B0, 1, 0); PG8_LDB(B1, 1, 1); PG8_SCHED; PG8_LDA(At, 1, 0); PG8_STAGE(PG8_SA(0, 1), a2 + hstepA, voffA);
;             PG8_WAIT_V(8); PG8_WAIT_L(0); PG8_BAR; PG8_MMA(0, 0, At, B0); PG8_MMA(0, 1, At, B1); PG8_BAR; PG8_SCHED;
;             PG8_LDA(At, 1, 1); PG8_STAGE(PG8_SB(1, 0), b3, voffB); PG8_STAGE(PG8_SB(1, 1), b3 + hstepB, voffB); PG8_STAGE(PG8_SA(1, 0), a3, voffA);
;             PG8_WAIT_V(8); PG8_WAIT_L(0); PG8_BAR; PG8_MMA(1, 0, At, B0); PG8_MMA(1, 1, At, B1); PG8_BAR; PG8_SCHED;
	s_cmp_eq_u32 s49, 15
	s_cselect_b32 s28, s50, s28
	s_cselect_b32 s29, s51, s29
	s_add_i32 m0, s2, 0x2000
	s_nop 0
	global_load_lds_dwordx4 v132, s[28:29]
	s_add_u32 s30, s28, 0x20000
	s_addc_u32 s31, s29, 0
	s_add_i32 m0, s2, 0x3000
	s_nop 0
	global_load_lds_dwordx4 v132, s[30:31]
	s_add_u32 s30, s28, 0x80000
	s_addc_u32 s31, s29, 0
	s_add_i32 m0, s2, 0x6000
	s_nop 0
	global_load_lds_dwordx4 v132, s[30:31]
	s_add_u32 s30, s28, 0xa0000
	s_addc_u32 s31, s29, 0
	s_add_i32 m0, s2, 0x7000
	s_nop 0
	global_load_lds_dwordx4 v132, s[30:31]
	s_add_u32 s34, s28, 0x80
	s_addc_u32 s35, s29, 0
	s_add_i32 m0, s2, 0x8000
	s_nop 0
	global_load_lds_dwordx4 v136, s[34:35]
	s_add_u32 s30, s34, 0x20000
	s_addc_u32 s31, s35, 0
	s_add_i32 m0, s2, 0x9000
	s_nop 0
	global_load_lds_dwordx4 v136, s[30:31]
	s_add_u32 s30, s34, 0x80000
	s_addc_u32 s31, s35, 0
	s_add_i32 m0, s2, 0xc000
	s_nop 0
	global_load_lds_dwordx4 v136, s[30:31]
	s_add_u32 s30, s34, 0xa0000
	s_addc_u32 s31, s35, 0
	s_add_i32 m0, s2, 0xd000
	s_nop 0
	global_load_lds_dwordx4 v136, s[30:31]
	s_add_u32 s28, s28, 0x80
	s_addc_u32 s29, s29, 0
	ds_read_b128 v[190:193], v155 offset:32768
	ds_read_b128 v[194:197], v155 offset:33792
	ds_read_b128 v[198:201], v155 offset:34816
	ds_read_b128 v[202:205], v155 offset:35840
	ds_read_b128 v[206:209], v155 offset:36864
	ds_read_b128 v[210:213], v155 offset:37888
	ds_read_b128 v[214:217], v155 offset:38912
	ds_read_b128 v[218:221], v155 offset:39936
	ds_read_b128 v[156:159], v153 offset:32768
	ds_read_b128 v[160:163], v153 offset:33792
	ds_read_b128 v[164:167], v153 offset:34816
	ds_read_b128 v[168:171], v153 offset:35840
	ds_read_b128 v[174:177], v153 offset:49152
	ds_read_b128 v[178:181], v153 offset:50176
	ds_read_b128 v[182:185], v153 offset:51200
	ds_read_b128 v[186:189], v153 offset:52224
	ds_read_b128 v[222:225], v155 offset:49152
	ds_read_b128 v[226:229], v155 offset:50176
	ds_read_b128 v[230:233], v155 offset:51200
	ds_read_b128 v[234:237], v155 offset:52224
	ds_read_b128 v[238:241], v155 offset:53248
	ds_read_b128 v[242:245], v155 offset:54272
	ds_read_b128 v[246:249], v155 offset:55296
	ds_read_b128 v[250:253], v155 offset:56320
	s_waitcnt vmcnt(8) lgkmcnt(0)
	s_barrier
	s_setprio 1
	v_mfma_f32_16x16x32_bf16 v[126:129], v[156:159], v[190:193], v[126:129]
	v_mfma_f32_16x16x32_bf16 v[126:129], v[160:163], v[194:197], v[126:129]
	v_mfma_f32_16x16x32_bf16 v[122:125], v[164:167], v[190:193], v[122:125]
	v_mfma_f32_16x16x32_bf16 v[122:125], v[168:171], v[194:197], v[122:125]
	v_mfma_f32_16x16x32_bf16 v[110:113], v[156:159], v[198:201], v[110:113]
	v_mfma_f32_16x16x32_bf16 v[110:113], v[160:163], v[202:205], v[110:113]
	v_mfma_f32_16x16x32_bf16 v[106:109], v[164:167], v[198:201], v[106:109]
	v_mfma_f32_16x16x32_bf16 v[106:109], v[168:171], v[202:205], v[106:109]
	v_mfma_f32_16x16x32_bf16 v[94:97], v[156:159], v[206:209], v[94:97]
	v_mfma_f32_16x16x32_bf16 v[94:97], v[160:163], v[210:213], v[94:97]
	v_mfma_f32_16x16x32_bf16 v[90:93], v[164:167], v[206:209], v[90:93]
	v_mfma_f32_16x16x32_bf16 v[90:93], v[168:171], v[210:213], v[90:93]
	v_mfma_f32_16x16x32_bf16 v[78:81], v[156:159], v[214:217], v[78:81]
	v_mfma_f32_16x16x32_bf16 v[78:81], v[160:163], v[218:221], v[78:81]
	v_mfma_f32_16x16x32_bf16 v[74:77], v[164:167], v[214:217], v[74:77]
	v_mfma_f32_16x16x32_bf16 v[74:77], v[168:171], v[218:221], v[74:77]
	v_mfma_f32_16x16x32_bf16 v[118:121], v[174:177], v[190:193], v[118:121]
	v_mfma_f32_16x16x32_bf16 v[118:121], v[178:181], v[194:197], v[118:121]
	v_mfma_f32_16x16x32_bf16 v[114:117], v[182:185], v[190:193], v[114:117]
	v_mfma_f32_16x16x32_bf16 v[114:117], v[186:189], v[194:197], v[114:117]
	v_mfma_f32_16x16x32_bf16 v[102:105], v[174:177], v[198:201], v[102:105]
	v_mfma_f32_16x16x32_bf16 v[102:105], v[178:181], v[202:205], v[102:105]
	v_mfma_f32_16x16x32_bf16 v[98:101], v[182:185], v[198:201], v[98:101]
	v_mfma_f32_16x16x32_bf16 v[98:101], v[186:189], v[202:205], v[98:101]
	v_mfma_f32_16x16x32_bf16 v[86:89], v[174:177], v[206:209], v[86:89]
	v_mfma_f32_16x16x32_bf16 v[86:89], v[178:181], v[210:213], v[86:89]
	v_mfma_f32_16x16x32_bf16 v[82:85], v[182:185], v[206:209], v[82:85]
	v_mfma_f32_16x16x32_bf16 v[82:85], v[186:189], v[210:213], v[82:85]
	v_mfma_f32_16x16x32_bf16 v[70:73], v[174:177], v[214:217], v[70:73]
	v_mfma_f32_16x16x32_bf16 v[70:73], v[178:181], v[218:221], v[70:73]
	v_mfma_f32_16x16x32_bf16 v[66:69], v[182:185], v[214:217], v[66:69]
	v_mfma_f32_16x16x32_bf16 v[66:69], v[186:189], v[218:221], v[66:69]
	v_mfma_f32_16x16x32_bf16 v[62:65], v[156:159], v[222:225], v[62:65]
	v_mfma_f32_16x16x32_bf16 v[62:65], v[160:163], v[226:229], v[62:65]
	v_mfma_f32_16x16x32_bf16 v[58:61], v[164:167], v[222:225], v[58:61]
	v_mfma_f32_16x16x32_bf16 v[58:61], v[168:171], v[226:229], v[58:61]
	v_mfma_f32_16x16x32_bf16 v[46:49], v[156:159], v[230:233], v[46:49]
	v_mfma_f32_16x16x32_bf16 v[46:49], v[160:163], v[234:237], v[46:49]
	v_mfma_f32_16x16x32_bf16 v[42:45], v[164:167], v[230:233], v[42:45]
	v_mfma_f32_16x16x32_bf16 v[42:45], v[168:171], v[234:237], v[42:45]
	v_mfma_f32_16x16x32_bf16 v[30:33], v[156:159], v[238:241], v[30:33]
	v_mfma_f32_16x16x32_bf16 v[30:33], v[160:163], v[242:245], v[30:33]
	v_mfma_f32_16x16x32_bf16 v[26:29], v[164:167], v[238:241], v[26:29]
	v_mfma_f32_16x16x32_bf16 v[26:29], v[168:171], v[242:245], v[26:29]
	v_mfma_f32_16x16x32_bf16 v[14:17], v[156:159], v[246:249], v[14:17]
	v_mfma_f32_16x16x32_bf16 v[14:17], v[160:163], v[250:253], v[14:17]
	v_mfma_f32_16x16x32_bf16 v[10:13], v[164:167], v[246:249], v[10:13]
	v_mfma_f32_16x16x32_bf16 v[10:13], v[168:171], v[250:253], v[10:13]
	v_mfma_f32_16x16x32_bf16 v[54:57], v[174:177], v[222:225], v[54:57]
	v_mfma_f32_16x16x32_bf16 v[54:57], v[178:181], v[226:229], v[54:57]
	v_mfma_f32_16x16x32_bf16 v[50:53], v[182:185], v[222:225], v[50:53]
	v_mfma_f32_16x16x32_bf16 v[50:53], v[186:189], v[226:229], v[50:53]
	v_mfma_f32_16x16x32_bf16 v[38:41], v[174:177], v[230:233], v[38:41]
	v_mfma_f32_16x16x32_bf16 v[38:41], v[178:181], v[234:237], v[38:41]
	v_mfma_f32_16x16x32_bf16 v[34:37], v[182:185], v[230:233], v[34:37]
	v_mfma_f32_16x16x32_bf16 v[34:37], v[186:189], v[234:237], v[34:37]
	v_mfma_f32_16x16x32_bf16 v[22:25], v[174:177], v[238:241], v[22:25]
	v_mfma_f32_16x16x32_bf16 v[22:25], v[178:181], v[242:245], v[22:25]
	v_mfma_f32_16x16x32_bf16 v[18:21], v[182:185], v[238:241], v[18:21]
	v_mfma_f32_16x16x32_bf16 v[18:21], v[186:189], v[242:245], v[18:21]
	v_mfma_f32_16x16x32_bf16 v[6:9], v[174:177], v[246:249], v[6:9]
	v_mfma_f32_16x16x32_bf16 v[6:9], v[178:181], v[250:253], v[6:9]
	v_mfma_f32_16x16x32_bf16 v[2:5], v[182:185], v[246:249], v[2:5]
	v_mfma_f32_16x16x32_bf16 v[2:5], v[186:189], v[250:253], v[2:5]
	s_setprio 0
	s_waitcnt vmcnt(0)
	s_barrier
	s_add_i32 s49, s49, 1
	s_cmp_lt_u32 s49, 16
	s_cbranch_scc1 .Lp8k_B_loop
